# norm phases: gain vector loads of each batch prefetched into freed prefetch registers during row 2
# baseline (speedup 1.0000x reference)
.LBB0_369:
	s_and_b64 vcc, exec, s[42:43]
	s_waitcnt vmcnt(2)
	v_mov_b32_e32 v52, v212
	v_mov_b32_e32 v53, v213
	v_mov_b32_e32 v54, v214
	v_mov_b32_e32 v55, v215
	v_mov_b32_e32 v56, v216
	v_mov_b32_e32 v57, v217
	v_mov_b32_e32 v58, v218
	v_mov_b32_e32 v59, v219
	global_load_dwordx4 v[204:207], v[90:91], off offset:16
	global_load_dwordx4 v[208:211], v[90:91], off
	global_load_dwordx4 v[212:215], v[90:91], off offset:2064
	global_load_dwordx4 v[216:219], v[90:91], off offset:2048
	v_lshlrev_b32_e32 v154, 16, v52
	v_and_b32_e32 v155, 0xffff0000, v52
	v_lshlrev_b32_e32 v156, 16, v53
	v_and_b32_e32 v157, 0xffff0000, v53
	v_lshlrev_b32_e32 v142, 16, v54
	v_and_b32_e32 v143, 0xffff0000, v54
	v_lshlrev_b32_e32 v144, 16, v55
	v_and_b32_e32 v145, 0xffff0000, v55
	s_waitcnt vmcnt(6)
	v_lshlrev_b32_e32 v146, 16, v56
	v_and_b32_e32 v147, 0xffff0000, v56
	v_lshlrev_b32_e32 v148, 16, v57
	v_and_b32_e32 v149, 0xffff0000, v57
	v_lshlrev_b32_e32 v150, 16, v58
	v_and_b32_e32 v151, 0xffff0000, v58
	v_lshlrev_b32_e32 v152, 16, v59
	v_and_b32_e32 v153, 0xffff0000, v59
	s_cbranch_vccnz .LBB0_371
	v_lshl_add_u64 v[56:57], v[88:89], 0, s[56:57]
	global_load_dwordx4 v[52:55], v[56:57], off
	s_waitcnt vmcnt(0)
	v_lshlrev_b32_e32 v58, 16, v52
	v_and_b32_e32 v59, 0xffff0000, v52
	v_lshlrev_b32_e32 v60, 16, v53
	v_and_b32_e32 v61, 0xffff0000, v53
	v_mul_f32_e32 v52, 0xbfb8aa3b, v58
	v_mul_f32_e32 v53, 0xbfb8aa3b, v59
	v_exp_f32_e32 v52, v52
	v_exp_f32_e32 v53, v53
	v_lshlrev_b32_e32 v62, 16, v54
	v_and_b32_e32 v54, 0xffff0000, v54
	v_add_f32_e32 v52, 1.0, v52
	v_add_f32_e32 v53, 1.0, v53
	v_rcp_f32_e32 v52, v52
	v_rcp_f32_e32 v53, v53
	v_lshlrev_b32_e32 v63, 16, v55
	v_and_b32_e32 v55, 0xffff0000, v55
	v_pk_mul_f32 v[154:155], v[52:53], v[154:155]
	v_mul_f32_e32 v52, 0xbfb8aa3b, v60
	v_mul_f32_e32 v53, 0xbfb8aa3b, v61
	v_exp_f32_e32 v52, v52
	v_exp_f32_e32 v53, v53
	v_add_f32_e32 v52, 1.0, v52
	v_add_f32_e32 v53, 1.0, v53
	v_rcp_f32_e32 v52, v52
	v_rcp_f32_e32 v53, v53
	s_nop 0
	v_pk_mul_f32 v[156:157], v[52:53], v[156:157]
	v_mul_f32_e32 v52, 0xbfb8aa3b, v62
	v_mul_f32_e32 v53, 0xbfb8aa3b, v54
	v_exp_f32_e32 v52, v52
	v_exp_f32_e32 v53, v53
	v_add_f32_e32 v52, 1.0, v52
	v_add_f32_e32 v53, 1.0, v53
	v_rcp_f32_e32 v52, v52
	v_rcp_f32_e32 v53, v53
	s_nop 0
	v_pk_mul_f32 v[142:143], v[52:53], v[142:143]
	v_mul_f32_e32 v52, 0xbfb8aa3b, v63
	v_mul_f32_e32 v53, 0xbfb8aa3b, v55
	v_exp_f32_e32 v52, v52
	v_exp_f32_e32 v53, v53
	v_add_f32_e32 v52, 1.0, v52
	v_add_f32_e32 v53, 1.0, v53
	v_rcp_f32_e32 v52, v52
	v_rcp_f32_e32 v53, v53
	s_nop 0
	v_pk_mul_f32 v[144:145], v[52:53], v[144:145]
	global_load_dwordx4 v[52:55], v[56:57], off offset:1024
	s_waitcnt vmcnt(0)
	v_lshlrev_b32_e32 v56, 16, v52
	v_and_b32_e32 v57, 0xffff0000, v52
	v_lshlrev_b32_e32 v58, 16, v53
	v_and_b32_e32 v59, 0xffff0000, v53
	v_mul_f32_e32 v52, 0xbfb8aa3b, v56
	v_mul_f32_e32 v53, 0xbfb8aa3b, v57
	v_exp_f32_e32 v52, v52
	v_exp_f32_e32 v53, v53
	v_lshlrev_b32_e32 v60, 16, v54
	v_and_b32_e32 v54, 0xffff0000, v54
	v_add_f32_e32 v52, 1.0, v52
	v_add_f32_e32 v53, 1.0, v53
	v_rcp_f32_e32 v52, v52
	v_rcp_f32_e32 v53, v53
	v_lshlrev_b32_e32 v61, 16, v55
	v_and_b32_e32 v55, 0xffff0000, v55
	v_pk_mul_f32 v[146:147], v[52:53], v[146:147]
	v_mul_f32_e32 v52, 0xbfb8aa3b, v58
	v_mul_f32_e32 v53, 0xbfb8aa3b, v59
	v_exp_f32_e32 v52, v52
	v_exp_f32_e32 v53, v53
	v_add_f32_e32 v52, 1.0, v52
	v_add_f32_e32 v53, 1.0, v53
	v_rcp_f32_e32 v52, v52
	v_rcp_f32_e32 v53, v53
	s_nop 0
	v_pk_mul_f32 v[148:149], v[52:53], v[148:149]
	v_mul_f32_e32 v52, 0xbfb8aa3b, v60
	v_mul_f32_e32 v53, 0xbfb8aa3b, v54
	v_exp_f32_e32 v52, v52
	v_exp_f32_e32 v53, v53
	v_add_f32_e32 v52, 1.0, v52
	v_add_f32_e32 v53, 1.0, v53
	v_rcp_f32_e32 v52, v52
	v_rcp_f32_e32 v53, v53
	s_nop 0
	v_pk_mul_f32 v[150:151], v[52:53], v[150:151]
	v_mul_f32_e32 v52, 0xbfb8aa3b, v61
	v_mul_f32_e32 v53, 0xbfb8aa3b, v55
	v_exp_f32_e32 v52, v52
	v_exp_f32_e32 v53, v53
	v_add_f32_e32 v52, 1.0, v52
	v_add_f32_e32 v53, 1.0, v53
	v_rcp_f32_e32 v52, v52
	v_rcp_f32_e32 v53, v53
	s_nop 0
	v_pk_mul_f32 v[152:153], v[52:53], v[152:153]

.LBB0_373:
	s_lshl_b64 s[58:59], s[36:37], 11
	s_waitcnt vmcnt(4)
	v_mov_b32_e32 v56, v228
	v_mov_b32_e32 v57, v229
	v_mov_b32_e32 v58, v230
	v_mov_b32_e32 v59, v231
	v_mov_b32_e32 v64, v232
	v_mov_b32_e32 v65, v233
	v_mov_b32_e32 v66, v234
	v_mov_b32_e32 v67, v235
	v_lshlrev_b32_e32 v52, 16, v56
	v_and_b32_e32 v53, 0xffff0000, v56
	v_lshlrev_b32_e32 v54, 16, v57
	v_and_b32_e32 v55, 0xffff0000, v57
	v_lshlrev_b32_e32 v56, 16, v58
	v_and_b32_e32 v57, 0xffff0000, v58
	v_lshlrev_b32_e32 v58, 16, v59
	v_and_b32_e32 v59, 0xffff0000, v59
	s_waitcnt vmcnt(4)
	v_lshlrev_b32_e32 v60, 16, v64
	v_and_b32_e32 v61, 0xffff0000, v64
	v_lshlrev_b32_e32 v62, 16, v65
	v_and_b32_e32 v63, 0xffff0000, v65
	v_lshlrev_b32_e32 v64, 16, v66
	v_and_b32_e32 v65, 0xffff0000, v66
	v_lshlrev_b32_e32 v66, 16, v67
	v_and_b32_e32 v67, 0xffff0000, v67
.LBB0_374:
	s_and_b64 vcc, exec, s[42:43]
	s_waitcnt vmcnt(4)
	v_mov_b32_e32 v68, v220
	v_mov_b32_e32 v69, v221
	v_mov_b32_e32 v70, v222
	v_mov_b32_e32 v71, v223
	v_mov_b32_e32 v72, v224
	v_mov_b32_e32 v73, v225
	v_mov_b32_e32 v74, v226
	v_mov_b32_e32 v75, v227
	v_lshlrev_b32_e32 v170, 16, v68
	v_and_b32_e32 v171, 0xffff0000, v68
	v_lshlrev_b32_e32 v172, 16, v69
	v_and_b32_e32 v173, 0xffff0000, v69
	v_lshlrev_b32_e32 v158, 16, v70
	v_and_b32_e32 v159, 0xffff0000, v70
	v_lshlrev_b32_e32 v160, 16, v71
	v_and_b32_e32 v161, 0xffff0000, v71
	s_waitcnt vmcnt(4)
	v_lshlrev_b32_e32 v162, 16, v72
	v_and_b32_e32 v163, 0xffff0000, v72
	v_lshlrev_b32_e32 v164, 16, v73
	v_and_b32_e32 v165, 0xffff0000, v73
	v_lshlrev_b32_e32 v166, 16, v74
	v_and_b32_e32 v167, 0xffff0000, v74
	v_lshlrev_b32_e32 v168, 16, v75
	v_and_b32_e32 v169, 0xffff0000, v75
	s_cbranch_vccnz .LBB0_376
	v_lshl_add_u64 v[72:73], v[88:89], 0, s[58:59]
	global_load_dwordx4 v[68:71], v[72:73], off
	s_waitcnt vmcnt(0)
	v_lshlrev_b32_e32 v74, 16, v68
	v_and_b32_e32 v75, 0xffff0000, v68
	v_lshlrev_b32_e32 v76, 16, v69
	v_and_b32_e32 v77, 0xffff0000, v69
	v_mul_f32_e32 v68, 0xbfb8aa3b, v74
	v_mul_f32_e32 v69, 0xbfb8aa3b, v75
	v_exp_f32_e32 v68, v68
	v_exp_f32_e32 v69, v69
	v_lshlrev_b32_e32 v78, 16, v70
	v_and_b32_e32 v70, 0xffff0000, v70
	v_add_f32_e32 v68, 1.0, v68
	v_add_f32_e32 v69, 1.0, v69
	v_rcp_f32_e32 v68, v68
	v_rcp_f32_e32 v69, v69
	v_lshlrev_b32_e32 v79, 16, v71
	v_and_b32_e32 v71, 0xffff0000, v71
	v_pk_mul_f32 v[170:171], v[68:69], v[170:171]
	v_mul_f32_e32 v68, 0xbfb8aa3b, v76
	v_mul_f32_e32 v69, 0xbfb8aa3b, v77
	v_exp_f32_e32 v68, v68
	v_exp_f32_e32 v69, v69
	v_add_f32_e32 v68, 1.0, v68
	v_add_f32_e32 v69, 1.0, v69
	v_rcp_f32_e32 v68, v68
	v_rcp_f32_e32 v69, v69
	s_nop 0
	v_pk_mul_f32 v[172:173], v[68:69], v[172:173]
	v_mul_f32_e32 v68, 0xbfb8aa3b, v78
	v_mul_f32_e32 v69, 0xbfb8aa3b, v70
	v_exp_f32_e32 v68, v68
	v_exp_f32_e32 v69, v69
	v_add_f32_e32 v68, 1.0, v68
	v_add_f32_e32 v69, 1.0, v69
	v_rcp_f32_e32 v68, v68
	v_rcp_f32_e32 v69, v69
	s_nop 0
	v_pk_mul_f32 v[158:159], v[68:69], v[158:159]
	v_mul_f32_e32 v68, 0xbfb8aa3b, v79
	v_mul_f32_e32 v69, 0xbfb8aa3b, v71
	v_exp_f32_e32 v68, v68
	v_exp_f32_e32 v69, v69
	v_add_f32_e32 v68, 1.0, v68
	v_add_f32_e32 v69, 1.0, v69
	v_rcp_f32_e32 v68, v68
	v_rcp_f32_e32 v69, v69
	s_nop 0
	v_pk_mul_f32 v[160:161], v[68:69], v[160:161]
	global_load_dwordx4 v[68:71], v[72:73], off offset:1024
	s_waitcnt vmcnt(0)
	v_lshlrev_b32_e32 v72, 16, v68
	v_and_b32_e32 v73, 0xffff0000, v68
	v_lshlrev_b32_e32 v74, 16, v69
	v_and_b32_e32 v75, 0xffff0000, v69
	v_mul_f32_e32 v68, 0xbfb8aa3b, v72
	v_mul_f32_e32 v69, 0xbfb8aa3b, v73
	v_exp_f32_e32 v68, v68
	v_exp_f32_e32 v69, v69
	v_lshlrev_b32_e32 v76, 16, v70
	v_and_b32_e32 v70, 0xffff0000, v70
	v_add_f32_e32 v68, 1.0, v68
	v_add_f32_e32 v69, 1.0, v69
	v_rcp_f32_e32 v68, v68
	v_rcp_f32_e32 v69, v69
	v_lshlrev_b32_e32 v77, 16, v71
	v_and_b32_e32 v71, 0xffff0000, v71
	v_pk_mul_f32 v[162:163], v[68:69], v[162:163]
	v_mul_f32_e32 v68, 0xbfb8aa3b, v74
	v_mul_f32_e32 v69, 0xbfb8aa3b, v75
	v_exp_f32_e32 v68, v68
	v_exp_f32_e32 v69, v69
	v_add_f32_e32 v68, 1.0, v68
	v_add_f32_e32 v69, 1.0, v69
	v_rcp_f32_e32 v68, v68
	v_rcp_f32_e32 v69, v69
	s_nop 0
	v_pk_mul_f32 v[164:165], v[68:69], v[164:165]
	v_mul_f32_e32 v68, 0xbfb8aa3b, v76
	v_mul_f32_e32 v69, 0xbfb8aa3b, v70
	v_exp_f32_e32 v68, v68
	v_exp_f32_e32 v69, v69
	v_add_f32_e32 v68, 1.0, v68
	v_add_f32_e32 v69, 1.0, v69
	v_rcp_f32_e32 v68, v68
	v_rcp_f32_e32 v69, v69
	s_nop 0
	v_pk_mul_f32 v[166:167], v[68:69], v[166:167]
	v_mul_f32_e32 v68, 0xbfb8aa3b, v77
	v_mul_f32_e32 v69, 0xbfb8aa3b, v71
	v_exp_f32_e32 v68, v68
	v_exp_f32_e32 v69, v69
	v_add_f32_e32 v68, 1.0, v68
	v_add_f32_e32 v69, 1.0, v69
	v_rcp_f32_e32 v68, v68
	v_rcp_f32_e32 v69, v69
	s_nop 0
	v_pk_mul_f32 v[168:169], v[68:69], v[168:169]
.LBB0_376:
	v_pk_mul_f32 v[68:69], v[114:115], v[114:115]
	v_pk_mul_f32 v[70:71], v[116:117], v[116:117]
	v_add_f32_e32 v68, v69, v68
	v_add_f32_e32 v68, v70, v68
	v_pk_mul_f32 v[72:73], v[110:111], v[110:111]
	v_add_f32_e32 v68, v71, v68
	v_add_f32_e32 v68, v72, v68
	v_pk_mul_f32 v[74:75], v[112:113], v[112:113]
	v_add_f32_e32 v68, v73, v68
	v_add_f32_e32 v68, v74, v68
	v_pk_mul_f32 v[76:77], v[106:107], v[106:107]
	v_add_f32_e32 v68, v75, v68
	v_add_f32_e32 v68, v76, v68
	v_pk_mul_f32 v[78:79], v[108:109], v[108:109]
	v_add_f32_e32 v68, v77, v68
	v_add_f32_e32 v68, v78, v68
	v_pk_mul_f32 v[80:81], v[102:103], v[102:103]
	v_add_f32_e32 v68, v79, v68
	v_add_f32_e32 v68, v80, v68
	v_pk_mul_f32 v[82:83], v[104:105], v[104:105]
	v_add_f32_e32 v68, v81, v68
	v_add_f32_e32 v68, v82, v68
	v_add_f32_e32 v191, v83, v68
	v_pk_mul_f32 v[68:69], v[130:131], v[130:131]
	v_pk_mul_f32 v[70:71], v[140:141], v[140:141]
	v_add_f32_e32 v68, v69, v68
	v_add_f32_e32 v68, v70, v68
	v_pk_mul_f32 v[72:73], v[118:119], v[118:119]
	v_add_f32_e32 v68, v71, v68
	v_add_f32_e32 v68, v72, v68
	v_pk_mul_f32 v[74:75], v[120:121], v[120:121]
	v_add_f32_e32 v68, v73, v68
	v_add_f32_e32 v68, v74, v68
	v_pk_mul_f32 v[76:77], v[122:123], v[122:123]
	v_add_f32_e32 v68, v75, v68
	v_add_f32_e32 v68, v76, v68
	v_pk_mul_f32 v[78:79], v[124:125], v[124:125]
	v_add_f32_e32 v68, v77, v68
	v_add_f32_e32 v68, v78, v68
	v_pk_mul_f32 v[80:81], v[126:127], v[126:127]
	v_add_f32_e32 v68, v79, v68
	v_add_f32_e32 v68, v80, v68
	v_pk_mul_f32 v[82:83], v[128:129], v[128:129]
	v_add_f32_e32 v68, v81, v68
	v_add_f32_e32 v68, v82, v68
	v_add_f32_e32 v192, v83, v68
	v_pk_mul_f32 v[68:69], v[154:155], v[154:155]
	v_pk_mul_f32 v[70:71], v[156:157], v[156:157]
	v_add_f32_e32 v68, v69, v68
	v_add_f32_e32 v68, v70, v68
	v_pk_mul_f32 v[72:73], v[142:143], v[142:143]
	v_add_f32_e32 v68, v71, v68
	v_add_f32_e32 v68, v72, v68
	v_pk_mul_f32 v[74:75], v[144:145], v[144:145]
	v_add_f32_e32 v68, v73, v68
	v_add_f32_e32 v68, v74, v68
	v_pk_mul_f32 v[76:77], v[146:147], v[146:147]
	v_add_f32_e32 v68, v75, v68
	v_add_f32_e32 v68, v76, v68
	v_pk_mul_f32 v[78:79], v[148:149], v[148:149]
	v_add_f32_e32 v68, v77, v68
	v_add_f32_e32 v68, v78, v68
	v_pk_mul_f32 v[80:81], v[150:151], v[150:151]
	v_add_f32_e32 v68, v79, v68
	v_add_f32_e32 v68, v80, v68
	v_pk_mul_f32 v[82:83], v[152:153], v[152:153]
	v_add_f32_e32 v68, v81, v68
	v_add_f32_e32 v68, v82, v68
	v_add_f32_e32 v193, v83, v68
	v_pk_mul_f32 v[68:69], v[170:171], v[170:171]
	v_pk_mul_f32 v[70:71], v[172:173], v[172:173]
	v_add_f32_e32 v68, v69, v68
	v_add_f32_e32 v68, v70, v68
	v_pk_mul_f32 v[72:73], v[158:159], v[158:159]
	v_add_f32_e32 v68, v71, v68
	v_add_f32_e32 v68, v72, v68
	v_pk_mul_f32 v[74:75], v[160:161], v[160:161]
	v_add_f32_e32 v68, v73, v68
	v_add_f32_e32 v68, v74, v68
	v_pk_mul_f32 v[76:77], v[162:163], v[162:163]
	v_add_f32_e32 v68, v75, v68
	v_add_f32_e32 v68, v76, v68
	v_pk_mul_f32 v[78:79], v[164:165], v[164:165]
	v_add_f32_e32 v68, v77, v68
	v_add_f32_e32 v68, v78, v68
	v_pk_mul_f32 v[80:81], v[166:167], v[166:167]
	v_add_f32_e32 v68, v79, v68
	v_add_f32_e32 v68, v80, v68
	v_pk_mul_f32 v[82:83], v[168:169], v[168:169]
	v_add_f32_e32 v68, v81, v68
	v_add_f32_e32 v68, v82, v68
	v_add_f32_e32 v68, v83, v68
	ds_bpermute_b32 v69, v132, v191
	ds_bpermute_b32 v72, v132, v68
	ds_bpermute_b32 v70, v132, v192
	ds_bpermute_b32 v71, v132, v193
	s_mov_b64 s[40:41], -1
	s_waitcnt lgkmcnt(3)
	v_add_f32_e32 v69, v191, v69
	s_waitcnt lgkmcnt(2)
	v_add_f32_e32 v68, v68, v72
	ds_bpermute_b32 v72, v139, v69
	s_waitcnt lgkmcnt(2)
	v_add_f32_e32 v70, v192, v70
	s_waitcnt lgkmcnt(1)
	v_add_f32_e32 v71, v193, v71
	s_waitcnt lgkmcnt(0)
	v_add_f32_e32 v69, v69, v72
	ds_bpermute_b32 v72, v139, v70
	s_waitcnt lgkmcnt(0)
	v_add_f32_e32 v70, v70, v72
	ds_bpermute_b32 v72, v139, v71
	s_waitcnt lgkmcnt(0)
	v_add_f32_e32 v71, v71, v72
	ds_bpermute_b32 v72, v139, v68
	s_waitcnt lgkmcnt(0)
	v_add_f32_e32 v68, v68, v72
	ds_bpermute_b32 v72, v187, v69
	s_waitcnt lgkmcnt(0)
	v_add_f32_e32 v69, v69, v72
	ds_bpermute_b32 v72, v187, v70
	s_waitcnt lgkmcnt(0)
	v_add_f32_e32 v70, v70, v72
	ds_bpermute_b32 v72, v187, v71
	s_waitcnt lgkmcnt(0)
	v_add_f32_e32 v71, v71, v72
	ds_bpermute_b32 v72, v187, v68
	s_waitcnt lgkmcnt(0)
	v_add_f32_e32 v68, v68, v72
	ds_bpermute_b32 v72, v188, v69
	s_waitcnt lgkmcnt(0)
	v_add_f32_e32 v69, v69, v72
	ds_bpermute_b32 v72, v188, v70
	s_waitcnt lgkmcnt(0)
	v_add_f32_e32 v70, v70, v72
	ds_bpermute_b32 v72, v188, v71
	s_waitcnt lgkmcnt(0)
	v_add_f32_e32 v71, v71, v72
	ds_bpermute_b32 v72, v188, v68
	s_waitcnt lgkmcnt(0)
	v_add_f32_e32 v68, v68, v72
	ds_bpermute_b32 v72, v189, v69
	s_waitcnt lgkmcnt(0)
	v_add_f32_e32 v69, v69, v72
	ds_bpermute_b32 v72, v189, v70
	s_waitcnt lgkmcnt(0)
	v_add_f32_e32 v195, v70, v72
	ds_bpermute_b32 v70, v189, v71
	ds_bpermute_b32 v196, v190, v195
	s_waitcnt lgkmcnt(1)
	v_add_f32_e32 v193, v71, v70
	ds_bpermute_b32 v70, v189, v68
	ds_bpermute_b32 v194, v190, v193
	s_waitcnt lgkmcnt(1)
	v_add_f32_e32 v191, v68, v70
	ds_bpermute_b32 v68, v190, v69
	ds_bpermute_b32 v192, v190, v191
	s_waitcnt lgkmcnt(1)
	v_add_f32_e32 v197, v69, v68
	v_fmamk_f32 v197, v197, 0x3a800000, v176
	v_cmp_gt_f32_e32 vcc, s75, v197
	v_mul_f32_e32 v198, 0x4b800000, v197
	s_nop 0
	v_cndmask_b32_e32 v197, v197, v198, vcc
	v_rsq_f32_e32 v197, v197
	s_nop 0
	v_mul_f32_e32 v198, 0x45800000, v197
	v_cndmask_b32_e32 v197, v197, v198, vcc
	v_mul_f32_e32 v198, v3, v197
	v_pk_mul_f32 v[114:115], v[114:115], v[198:199] op_sel_hi:[1,0]
	v_pk_mul_f32 v[110:111], v[110:111], v[198:199] op_sel_hi:[1,0]
	v_pk_mul_f32 v[106:107], v[106:107], v[198:199] op_sel_hi:[1,0]
	v_pk_mul_f32 v[102:103], v[102:103], v[198:199] op_sel_hi:[1,0]
	s_and_b64 vcc, exec, s[46:47]
	s_waitcnt vmcnt(0)
	v_mov_b32_e32 v68, v204
	v_mov_b32_e32 v69, v205
	v_mov_b32_e32 v70, v206
	v_mov_b32_e32 v71, v207
	v_mov_b32_e32 v72, v208
	v_mov_b32_e32 v73, v209
	v_mov_b32_e32 v74, v210
	v_mov_b32_e32 v75, v211
	v_mov_b32_e32 v76, v212
	v_mov_b32_e32 v77, v213
	v_mov_b32_e32 v78, v214
	v_mov_b32_e32 v79, v215
	v_mov_b32_e32 v80, v216
	v_mov_b32_e32 v81, v217
	v_mov_b32_e32 v82, v218
	v_mov_b32_e32 v83, v219
	v_pk_fma_f32 v[12:13], v[68:69], v[110:111], v[12:13]
	s_waitcnt vmcnt(2)
	v_pk_fma_f32 v[16:17], v[72:73], v[114:115], v[16:17]
	v_pk_mul_f32 v[114:115], v[116:117], v[198:199] op_sel_hi:[1,0]
	v_pk_mul_f32 v[110:111], v[112:113], v[198:199] op_sel_hi:[1,0]
	s_waitcnt vmcnt(0)
	v_pk_fma_f32 v[8:9], v[80:81], v[106:107], v[8:9]
	v_pk_mul_f32 v[106:107], v[108:109], v[198:199] op_sel_hi:[1,0]
	v_pk_fma_f32 v[4:5], v[76:77], v[102:103], v[4:5]
	v_pk_mul_f32 v[102:103], v[104:105], v[198:199] op_sel_hi:[1,0]
	v_pk_fma_f32 v[18:19], v[74:75], v[114:115], v[18:19]
	v_pk_fma_f32 v[14:15], v[70:71], v[110:111], v[14:15]
	v_pk_fma_f32 v[10:11], v[82:83], v[106:107], v[10:11]
	v_pk_fma_f32 v[6:7], v[78:79], v[102:103], v[6:7]
	s_cbranch_vccz .LBB0_378
	s_mov_b64 s[40:41], 0
	global_store_dwordx4 v[98:99], v[16:19], off offset:-2064
	global_store_dwordx4 v[98:99], v[12:15], off offset:-2048
	global_store_dwordx4 v[98:99], v[8:11], off offset:-16
	global_store_dwordx4 v[98:99], v[4:7], off
